# G1 epilogue: bj=1 half reuses the bj=0 code (second pass, accumulators moved), halving cold epilogue code; plus SEC7/8 shared body, SEC2 LDS transpose, SEC4 grouped loads
# baseline (speedup 1.0000x reference)
.Lsec_chain:
	s_cmpk_lt_u32 s74, 0x400
	s_mov_b32 s2, 1
	s_cbranch_scc1 .LBB0_60
	s_cmpk_lt_u32 s74, 0x800
	s_mov_b32 s2, 2
	s_cbranch_scc1 .LBB0_60
	s_cmpk_lt_u32 s74, 0xc00
	s_mov_b32 s2, 3
	s_cbranch_scc1 .LBB0_60
	s_cmpk_lt_u32 s74, 0x1300
	s_cselect_b32 s0, 7, 8
	s_cmpk_gt_u32 s74, 0xeff
	s_cselect_b32 s0, s0, 6
	s_cmpk_gt_u32 s74, 0xe7f
	s_cselect_b32 s0, s0, 5
	s_cmpk_gt_u32 s74, 0xdff
	s_cselect_b32 s2, s0, 4

.LBB0_158:
	s_andn2_b64 vcc, exec, s[0:1]
	s_cbranch_vccnz .LBB0_166
	s_cmp_gt_i32 s2, 0
	s_mov_b64 s[0:1], -1
	s_cbranch_scc0 .LBB0_163
	s_or_b32 s0, s74, s49
	s_lshr_b32 s1, s0, 6
	s_and_b32 s2, s1, 7
	s_lshl_b32 s1, s2, 2
	v_mov_b32_e32 v2, s1
	global_load_dword v132, v2, s[80:81]
	s_lshl_b32 s3, s48, 8
	global_load_dword v2, v2, s[80:81] offset:32
	s_add_i32 s3, s3, s31
	v_or_b32_e32 v206, s3, v181
	v_bitop3_b32 v220, s3, v250, v181 bitop3:0xc8
	v_cmp_gt_i32_e64 s[44:45], s20, v206
	v_or_b32_e32 v188, s0, v242
	v_bitop3_b32 v216, s0, 56, v242 bitop3:0xc8
	v_readlane_b32 s0, v251, 9
	v_ashrrev_i32_e32 v207, 31, v206
	v_readlane_b32 s1, v251, 10
	s_movk_i32 s4, 0x7df
	v_or_b32_e32 v190, 16, v206
	v_bitop3_b32 v218, v206, s4, 16 bitop3:0xc8
	v_cmp_gt_i32_e64 s[42:43], s20, v190
	s_movk_i32 s4, 0x7ef
	v_or_b32_e32 v160, 32, v206
	v_bitop3_b32 v163, v206, s4, 32 bitop3:0xc8
	v_cmp_gt_i32_e64 s[40:41], s20, v160
	s_movk_i32 s4, 0x7ff
	v_or_b32_e32 v156, 48, v206
	v_bitop3_b32 v159, v206, s4, 48 bitop3:0xc8
	v_ashrrev_i32_e32 v189, 31, v188
	v_cmp_gt_i32_e32 vcc, s20, v156
	v_lshlrev_b64 v[188:189], 1, v[188:189]
	s_mov_b32 s47, 0x101f000
	s_ashr_i32 s4, s3, 11
	v_add_u32_e32 v168, 0x80, v220
	v_readlane_b32 s16, v251, 7
	v_readlane_b32 s17, v251, 8
	s_movk_i32 s36, 0x1000
	s_movk_i32 s21, 0x2000
	s_movk_i32 s37, 0x3000
	v_or_b32_e32 v193, 4, v216
	v_ashrrev_i32_e32 v191, 31, v190
	v_ashrrev_i32_e32 v161, 31, v160
	v_ashrrev_i32_e32 v157, 31, v156
	s_waitcnt vmcnt(0)
	v_mul_f32_e32 v132, 0x3fb8aa3b, v132
	v_exp_f32_e32 v212, v132
	v_mul_f32_e32 v2, 0x3fb8aa3b, v2
	v_exp_f32_e32 v214, v2
	v_or_b32_e32 v2, 16, v220
	v_cndmask_b32_e64 v2, v181, v2, s[44:45]
	v_lshlrev_b32_e32 v2, 8, v2
	v_lshl_add_u64 v[132:133], v[206:207], 2, s[70:71]
	v_lshl_add_u64 v[134:135], s[0:1], 0, v[2:3]
	v_lshlrev_b32_e32 v2, 2, v216
	global_load_dword v194, v[132:133], off
	v_lshl_add_u64 v[134:135], v[134:135], 0, v[2:3]
	global_load_dwordx4 v[234:237], v[134:135], off offset:16
	global_load_dwordx4 v[196:199], v[134:135], off
	v_add_u32_e32 v134, 16, v218
	v_cndmask_b32_e64 v134, v181, v134, s[42:43]
	v_lshlrev_b32_e32 v134, 8, v134
	v_mov_b32_e32 v135, v3
	v_lshl_add_u64 v[134:135], s[0:1], 0, v[134:135]
	global_load_dword v192, v[132:133], off offset:64
	v_lshl_add_u64 v[134:135], v[134:135], 0, v[2:3]
	global_load_dwordx4 v[148:151], v[134:135], off offset:16
	global_load_dwordx4 v[152:155], v[134:135], off
	v_or_b32_e32 v134, 16, v163
	v_cndmask_b32_e64 v134, v181, v134, s[40:41]
	v_lshlrev_b32_e32 v134, 8, v134
	v_mov_b32_e32 v135, v3
	v_lshl_add_u64 v[134:135], s[0:1], 0, v[134:135]
	v_lshl_add_u64 v[134:135], v[134:135], 0, v[2:3]
	global_load_dword v162, v[132:133], off offset:128
	global_load_dwordx4 v[140:143], v[134:135], off offset:16
	global_load_dwordx4 v[144:147], v[134:135], off
	global_load_dword v158, v[132:133], off offset:192
	v_add_u32_e32 v132, 16, v159
	v_lshlrev_b64 v[206:207], 10, v[206:207]
	v_cndmask_b32_e32 v132, v181, v132, vcc
	v_lshl_add_u64 v[206:207], s[94:95], 0, v[206:207]
	v_lshlrev_b32_e32 v132, 8, v132
	v_mov_b32_e32 v133, v3
	v_lshl_add_u64 v[206:207], v[206:207], 0, v[188:189]
	v_lshl_add_u64 v[132:133], s[0:1], 0, v[132:133]
	v_add_co_u32_e64 v206, s[0:1], s47, v206
	v_lshl_add_u64 v[136:137], v[132:133], 0, v[2:3]
	s_nop 0
	v_addc_co_u32_e64 v207, s[0:1], 0, v207, s[0:1]
	s_add_i32 s0, s3, 0xffffc000
	s_lshr_b32 s0, s0, 4
	v_mov_b32_e32 v169, s0
	global_load_dwordx4 v[132:135], v[136:137], off offset:16
	s_nop 0
	global_load_dwordx4 v[136:139], v[136:137], off
	s_waitcnt vmcnt(0)
	v_pk_mul_f32 v[202:203], v[128:129], v[194:195] op_sel_hi:[1,0]
	v_pk_mul_f32 v[200:201], v[130:131], v[194:195] op_sel_hi:[1,0]
	v_pk_mul_f32 v[204:205], v[196:197], v[202:203] op_sel:[1,1] op_sel_hi:[1,0]
	v_pk_mul_f32 v[222:223], v[126:127], v[194:195] op_sel_hi:[1,0]
	v_pk_fma_f32 v[210:211], v[196:197], v[202:203], v[204:205] op_sel_hi:[0,1,1] neg_lo:[0,0,1] neg_hi:[0,0,1]
	v_pk_fma_f32 v[208:209], v[196:197], v[202:203], v[204:205] op_sel_hi:[0,1,1]
	v_mov_b32_e32 v196, v199
	v_pk_mul_f32 v[196:197], v[196:197], v[200:201] op_sel:[0,1] op_sel_hi:[0,0]
	v_pk_mul_f32 v[194:195], v[124:125], v[194:195] op_sel_hi:[1,0]
	v_pk_fma_f32 v[204:205], v[198:199], v[200:201], v[196:197] op_sel_hi:[0,1,1] neg_lo:[0,0,1] neg_hi:[0,0,1]
	v_pk_fma_f32 v[202:203], v[198:199], v[200:201], v[196:197] op_sel_hi:[0,1,1]
	v_pk_mul_f32 v[196:197], v[234:235], v[194:195] op_sel:[1,1] op_sel_hi:[1,0]
	s_nop 0
	v_pk_fma_f32 v[200:201], v[234:235], v[194:195], v[196:197] op_sel_hi:[0,1,1] neg_lo:[0,0,1] neg_hi:[0,0,1]
	v_pk_fma_f32 v[198:199], v[234:235], v[194:195], v[196:197] op_sel_hi:[0,1,1]
	v_mov_b32_e32 v194, v237
	v_pk_mul_f32 v[194:195], v[194:195], v[222:223] op_sel:[0,1] op_sel_hi:[0,0]
	v_pk_fma_f32 v[196:197], v[236:237], v[222:223], v[194:195] op_sel_hi:[0,1,1] neg_lo:[0,0,1] neg_hi:[0,0,1]
	v_pk_fma_f32 v[194:195], v[236:237], v[222:223], v[194:195] op_sel_hi:[0,1,1]
	v_cvt_pk_bf16_f32 v234, v210, v209
	v_cvt_pk_bf16_f32 v235, v204, v203
	v_cvt_pk_bf16_f32 v236, v200, v199
	v_cvt_pk_bf16_f32 v237, v196, v195
	v_mov_b32_e32 v194, s4
	global_store_dwordx4 v[206:207], v[234:237], off offset:3072
	v_cndmask_b32_e64 v169, v169, v194, s[44:45]
	v_cndmask_b32_e64 v206, v244, v168, s[44:45]
	s_movk_i32 s44, 0x7f
	v_bitop3_b32 v197, v206, s44, v206 bitop3:0xc
	v_cvt_f32_ubyte0_e32 v197, v197
	v_and_b32_e32 v168, 0x7f, v206
	v_mul_f32_e64 v197, v197, -v212
	v_lshl_or_b32 v220, v169, 3, s2
	v_mul_f32_e32 v197, 0x3fb8aa3b, v197
	v_cvt_f32_ubyte0_e32 v168, v168
	v_ashrrev_i32_e32 v221, 31, v220
	v_exp_f32_e32 v215, v197
	v_mul_f32_e64 v168, v168, -v214
	v_lshlrev_b64 v[220:221], 6, v[220:221]
	v_mul_f32_e32 v168, 0x3fb8aa3b, v168
	v_or_b32_e32 v169, v220, v216
	v_mov_b32_e32 v207, v3
	s_movk_i32 s45, 0x880
	v_exp_f32_e32 v168, v168
	v_mad_u64_u32 v[222:223], s[0:1], v169, s45, v[206:207]
	v_mad_i32_i24 v223, v221, s45, v223
	v_lshlrev_b64 v[222:223], 1, v[222:223]
	v_mul_f32_e32 v169, v215, v210
	v_lshl_add_u64 v[234:235], s[16:17], 0, v[222:223]
	v_readlane_b32 s4, v251, 5
	v_cvt_pk_bf16_f32 v169, v169, s0
	v_readlane_b32 s5, v251, 6
	global_store_short v[234:235], v169, off
	v_mul_f32_e32 v169, v168, v210
	v_lshl_add_u64 v[222:223], s[4:5], 0, v[222:223]
	v_cvt_pk_bf16_f32 v169, v169, s0
	global_store_short v[222:223], v169, off
	v_mul_f32_e32 v169, v215, v209
	v_cvt_pk_bf16_f32 v169, v169, s0
	v_add_co_u32_e64 v210, s[0:1], s36, v234
	s_nop 1
	v_addc_co_u32_e64 v211, s[0:1], 0, v235, s[0:1]
	global_store_short v[210:211], v169, off offset:256
	v_mul_f32_e32 v169, v168, v209
	v_cvt_pk_bf16_f32 v169, v169, s0
	v_add_co_u32_e64 v208, s[0:1], s36, v222
	s_nop 1
	v_addc_co_u32_e64 v209, s[0:1], 0, v223, s[0:1]
	global_store_short v[208:209], v169, off offset:256
	v_mul_f32_e32 v169, v215, v204
	v_cvt_pk_bf16_f32 v169, v169, s0
	v_add_co_u32_e64 v208, s[0:1], s21, v234
	s_nop 1
	v_addc_co_u32_e64 v209, s[0:1], 0, v235, s[0:1]
	global_store_short v[208:209], v169, off offset:512
	v_mul_f32_e32 v169, v168, v204
	v_cvt_pk_bf16_f32 v169, v169, s0
	v_add_co_u32_e64 v204, s[0:1], s21, v222
	s_nop 1
	v_addc_co_u32_e64 v205, s[0:1], 0, v223, s[0:1]
	global_store_short v[204:205], v169, off offset:512
	v_mul_f32_e32 v169, v215, v203
	v_cvt_pk_bf16_f32 v169, v169, s0
	v_add_co_u32_e64 v204, s[0:1], s37, v234
	s_nop 1
	v_addc_co_u32_e64 v205, s[0:1], 0, v235, s[0:1]
	global_store_short v[204:205], v169, off offset:768
	v_mul_f32_e32 v169, v168, v203
	v_cvt_pk_bf16_f32 v169, v169, s0
	v_add_co_u32_e64 v202, s[0:1], s37, v222
	s_nop 1
	v_addc_co_u32_e64 v203, s[0:1], 0, v223, s[0:1]
	global_store_short v[202:203], v169, off offset:768
	v_or_b32_e32 v169, v220, v193
	v_mad_u64_u32 v[202:203], s[0:1], v169, s45, v[206:207]
	v_mad_i32_i24 v203, v221, s45, v203
	v_lshlrev_b64 v[202:203], 1, v[202:203]
	v_mul_f32_e32 v169, v215, v200
	v_lshl_add_u64 v[204:205], s[16:17], 0, v[202:203]
	v_cvt_pk_bf16_f32 v169, v169, s0
	global_store_short v[204:205], v169, off
	v_mul_f32_e32 v169, v168, v200
	v_lshl_add_u64 v[202:203], s[4:5], 0, v[202:203]
	v_cvt_pk_bf16_f32 v169, v169, s0
	global_store_short v[202:203], v169, off
	v_mul_f32_e32 v169, v215, v199
	v_cvt_pk_bf16_f32 v169, v169, s0
	v_add_co_u32_e64 v200, s[0:1], s36, v204
	s_nop 1
	v_addc_co_u32_e64 v201, s[0:1], 0, v205, s[0:1]
	global_store_short v[200:201], v169, off offset:256
	v_mul_f32_e32 v169, v168, v199
	v_cvt_pk_bf16_f32 v169, v169, s0
	v_add_co_u32_e64 v198, s[0:1], s36, v202
	s_nop 1
	v_addc_co_u32_e64 v199, s[0:1], 0, v203, s[0:1]
	global_store_short v[198:199], v169, off offset:256
	v_mul_f32_e32 v169, v215, v196
	v_cvt_pk_bf16_f32 v169, v169, s0
	v_add_co_u32_e64 v198, s[0:1], s21, v204
	s_nop 1
	v_addc_co_u32_e64 v199, s[0:1], 0, v205, s[0:1]
	global_store_short v[198:199], v169, off offset:512
	v_mul_f32_e32 v169, v168, v196
	v_cvt_pk_bf16_f32 v169, v169, s0
	v_add_co_u32_e64 v196, s[0:1], s21, v202
	v_mul_f32_e32 v168, v168, v195
	s_nop 0
	v_addc_co_u32_e64 v197, s[0:1], 0, v203, s[0:1]
	global_store_short v[196:197], v169, off offset:512
	v_mul_f32_e32 v169, v215, v195
	v_cvt_pk_bf16_f32 v169, v169, s0
	v_add_co_u32_e64 v196, s[0:1], s37, v204
	v_pk_mul_f32 v[198:199], v[120:121], v[192:193] op_sel_hi:[1,0]
	s_nop 0
	v_addc_co_u32_e64 v197, s[0:1], 0, v205, s[0:1]
	global_store_short v[196:197], v169, off offset:768
	s_nop 0
	v_cvt_pk_bf16_f32 v168, v168, s0
	v_add_co_u32_e64 v196, s[0:1], s37, v202
	v_pk_mul_f32 v[200:201], v[152:153], v[198:199] op_sel:[1,1] op_sel_hi:[1,0]
	s_nop 0
	v_addc_co_u32_e64 v197, s[0:1], 0, v203, s[0:1]
	v_pk_fma_f32 v[202:203], v[152:153], v[198:199], v[200:201] op_sel_hi:[0,1,1] neg_lo:[0,0,1] neg_hi:[0,0,1]
	v_pk_fma_f32 v[152:153], v[152:153], v[198:199], v[200:201] op_sel_hi:[0,1,1]
	global_store_short v[196:197], v168, off offset:768
	v_pk_mul_f32 v[196:197], v[122:123], v[192:193] op_sel_hi:[1,0]
	v_mov_b32_e32 v152, v155
	v_pk_mul_f32 v[198:199], v[152:153], v[196:197] op_sel:[0,1] op_sel_hi:[0,0]
	v_pk_fma_f32 v[200:201], v[154:155], v[196:197], v[198:199] op_sel_hi:[0,1,1] neg_lo:[0,0,1] neg_hi:[0,0,1]
	v_pk_fma_f32 v[154:155], v[154:155], v[196:197], v[198:199] op_sel_hi:[0,1,1]
	v_pk_mul_f32 v[198:199], v[116:117], v[192:193] op_sel_hi:[1,0]
	v_pk_mul_f32 v[196:197], v[118:119], v[192:193] op_sel_hi:[1,0]
	v_pk_mul_f32 v[204:205], v[148:149], v[198:199] op_sel:[1,1] op_sel_hi:[1,0]
	s_nop 0
	v_pk_fma_f32 v[206:207], v[148:149], v[198:199], v[204:205] op_sel_hi:[0,1,1] neg_lo:[0,0,1] neg_hi:[0,0,1]
	v_pk_fma_f32 v[198:199], v[148:149], v[198:199], v[204:205] op_sel_hi:[0,1,1]
	v_mov_b32_e32 v148, v151
	v_pk_mul_f32 v[148:149], v[148:149], v[196:197] op_sel:[0,1] op_sel_hi:[0,0]
	v_pk_fma_f32 v[204:205], v[150:151], v[196:197], v[148:149] op_sel_hi:[0,1,1] neg_lo:[0,0,1] neg_hi:[0,0,1]
	v_pk_fma_f32 v[196:197], v[150:151], v[196:197], v[148:149] op_sel_hi:[0,1,1]
	v_lshlrev_b64 v[148:149], 10, v[190:191]
	v_lshl_add_u64 v[148:149], s[94:95], 0, v[148:149]
	v_lshl_add_u64 v[190:191], v[148:149], 0, v[188:189]
	v_add_co_u32_e64 v190, s[0:1], s47, v190
	v_cvt_pk_bf16_f32 v148, v202, v153
	v_cvt_pk_bf16_f32 v149, v200, v155
	v_cvt_pk_bf16_f32 v150, v206, v199
	v_cvt_pk_bf16_f32 v151, v204, v197
	v_addc_co_u32_e64 v191, s[0:1], 0, v191, s[0:1]
	global_store_dwordx4 v[190:191], v[148:151], off offset:3072
	s_add_i32 s0, s3, 0xffffc010
	s_lshr_b32 s0, s0, 4
	v_add_u32_e32 v148, 0x80, v218
	v_cndmask_b32_e64 v148, v244, v148, s[42:43]
	v_and_b32_e32 v150, 0x7f, v148
	v_bitop3_b32 v151, v148, s44, v148 bitop3:0xc
	v_cvt_f32_ubyte0_e32 v150, v150
	v_mov_b32_e32 v149, s0
	v_cvt_f32_ubyte0_e32 v151, v151
	v_mul_f32_e64 v150, v150, -v214
	v_cndmask_b32_e64 v149, v149, v194, s[42:43]
	v_mul_f32_e64 v151, v151, -v212
	v_mul_f32_e32 v150, 0x3fb8aa3b, v150
	v_mul_f32_e32 v151, 0x3fb8aa3b, v151
	v_exp_f32_e32 v168, v150
	v_lshl_or_b32 v150, v149, 3, s2
	v_exp_f32_e32 v154, v151
	v_ashrrev_i32_e32 v151, 31, v150
	v_lshlrev_b64 v[150:151], 6, v[150:151]
	v_or_b32_e32 v152, v150, v216
	v_mov_b32_e32 v149, v3
	v_mad_u64_u32 v[190:191], s[0:1], v152, s45, v[148:149]
	v_mad_i32_i24 v191, v151, s45, v191
	v_lshlrev_b64 v[190:191], 1, v[190:191]
	v_mul_f32_e32 v152, v154, v202
	v_lshl_add_u64 v[208:209], s[16:17], 0, v[190:191]
	v_cvt_pk_bf16_f32 v152, v152, s0
	global_store_short v[208:209], v152, off
	v_mul_f32_e32 v152, v168, v202
	v_lshl_add_u64 v[190:191], s[4:5], 0, v[190:191]
	v_cvt_pk_bf16_f32 v152, v152, s0
	global_store_short v[190:191], v152, off
	v_mul_f32_e32 v152, v154, v153
	v_cvt_pk_bf16_f32 v152, v152, s0
	v_add_co_u32_e64 v202, s[0:1], s36, v208
	v_or_b32_e32 v150, v150, v193
	s_nop 0
	v_addc_co_u32_e64 v203, s[0:1], 0, v209, s[0:1]
	global_store_short v[202:203], v152, off offset:256
	v_mul_f32_e32 v152, v168, v153
	v_cvt_pk_bf16_f32 v169, v152, s0
	v_add_co_u32_e64 v152, s[0:1], s36, v190
	s_nop 1
	v_addc_co_u32_e64 v153, s[0:1], 0, v191, s[0:1]
	global_store_short v[152:153], v169, off offset:256
	v_mul_f32_e32 v152, v154, v200
	v_cvt_pk_bf16_f32 v169, v152, s0
	v_add_co_u32_e64 v152, s[0:1], s21, v208
	s_nop 1
	v_addc_co_u32_e64 v153, s[0:1], 0, v209, s[0:1]
	global_store_short v[152:153], v169, off offset:512
	v_mul_f32_e32 v152, v168, v200
	v_cvt_pk_bf16_f32 v169, v152, s0
	v_add_co_u32_e64 v152, s[0:1], s21, v190
	s_nop 1
	v_addc_co_u32_e64 v153, s[0:1], 0, v191, s[0:1]
	global_store_short v[152:153], v169, off offset:512
	v_mul_f32_e32 v152, v154, v155
	v_cvt_pk_bf16_f32 v169, v152, s0
	v_add_co_u32_e64 v152, s[0:1], s37, v208
	s_nop 1
	v_addc_co_u32_e64 v153, s[0:1], 0, v209, s[0:1]
	global_store_short v[152:153], v169, off offset:768
	v_mul_f32_e32 v152, v168, v155
	v_cvt_pk_bf16_f32 v155, v152, s0
	v_add_co_u32_e64 v152, s[0:1], s37, v190
	s_nop 1
	v_addc_co_u32_e64 v153, s[0:1], 0, v191, s[0:1]
	v_mad_u64_u32 v[148:149], s[0:1], v150, s45, v[148:149]
	v_mad_i32_i24 v149, v151, s45, v149
	global_store_short v[152:153], v155, off offset:768
	v_lshlrev_b64 v[148:149], 1, v[148:149]
	v_mul_f32_e32 v152, v154, v206
	v_lshl_add_u64 v[150:151], s[16:17], 0, v[148:149]
	v_cvt_pk_bf16_f32 v152, v152, s0
	global_store_short v[150:151], v152, off
	v_mul_f32_e32 v152, v168, v206
	v_lshl_add_u64 v[148:149], s[4:5], 0, v[148:149]
	v_cvt_pk_bf16_f32 v152, v152, s0
	global_store_short v[148:149], v152, off
	v_mul_f32_e32 v152, v154, v199
	v_cvt_pk_bf16_f32 v155, v152, s0
	v_add_co_u32_e64 v152, s[0:1], s36, v150
	s_nop 1
	v_addc_co_u32_e64 v153, s[0:1], 0, v151, s[0:1]
	global_store_short v[152:153], v155, off offset:256
	v_mul_f32_e32 v152, v168, v199
	v_cvt_pk_bf16_f32 v155, v152, s0
	v_add_co_u32_e64 v152, s[0:1], s36, v148
	s_nop 1
	v_addc_co_u32_e64 v153, s[0:1], 0, v149, s[0:1]
	global_store_short v[152:153], v155, off offset:256
	v_mul_f32_e32 v152, v154, v204
	v_cvt_pk_bf16_f32 v155, v152, s0
	v_add_co_u32_e64 v152, s[0:1], s21, v150
	s_nop 1
	v_addc_co_u32_e64 v153, s[0:1], 0, v151, s[0:1]
	global_store_short v[152:153], v155, off offset:512
	v_mul_f32_e32 v152, v168, v204
	v_cvt_pk_bf16_f32 v155, v152, s0
	v_add_co_u32_e64 v152, s[0:1], s21, v148
	s_nop 1
	v_addc_co_u32_e64 v153, s[0:1], 0, v149, s[0:1]
	global_store_short v[152:153], v155, off offset:512
	v_mul_f32_e32 v152, v154, v197
	v_cvt_pk_bf16_f32 v152, v152, s0
	v_add_co_u32_e64 v150, s[0:1], s37, v150
	s_nop 1
	v_addc_co_u32_e64 v151, s[0:1], 0, v151, s[0:1]
	global_store_short v[150:151], v152, off offset:768
	v_mul_f32_e32 v150, v168, v197
	v_cvt_pk_bf16_f32 v150, v150, s0
	v_add_co_u32_e64 v148, s[0:1], s37, v148
	s_nop 1
	v_addc_co_u32_e64 v149, s[0:1], 0, v149, s[0:1]
	global_store_short v[148:149], v150, off offset:768
	v_pk_mul_f32 v[150:151], v[112:113], v[162:163] op_sel_hi:[1,0]
	v_pk_mul_f32 v[148:149], v[114:115], v[162:163] op_sel_hi:[1,0]
	v_pk_mul_f32 v[152:153], v[144:145], v[150:151] op_sel:[1,1] op_sel_hi:[1,0]
	s_nop 0
	v_pk_fma_f32 v[154:155], v[144:145], v[150:151], v[152:153] op_sel_hi:[0,1,1] neg_lo:[0,0,1] neg_hi:[0,0,1]
	v_pk_fma_f32 v[144:145], v[144:145], v[150:151], v[152:153] op_sel_hi:[0,1,1]
	v_mov_b32_e32 v144, v147
	v_pk_mul_f32 v[150:151], v[144:145], v[148:149] op_sel:[0,1] op_sel_hi:[0,0]
	v_pk_fma_f32 v[152:153], v[146:147], v[148:149], v[150:151] op_sel_hi:[0,1,1] neg_lo:[0,0,1] neg_hi:[0,0,1]
	v_pk_fma_f32 v[146:147], v[146:147], v[148:149], v[150:151] op_sel_hi:[0,1,1]
	v_pk_mul_f32 v[150:151], v[108:109], v[162:163] op_sel_hi:[1,0]
	v_pk_mul_f32 v[148:149], v[110:111], v[162:163] op_sel_hi:[1,0]
	v_pk_mul_f32 v[190:191], v[140:141], v[150:151] op_sel:[1,1] op_sel_hi:[1,0]
	s_nop 0
	v_pk_fma_f32 v[196:197], v[140:141], v[150:151], v[190:191] op_sel_hi:[0,1,1] neg_lo:[0,0,1] neg_hi:[0,0,1]
	v_pk_fma_f32 v[150:151], v[140:141], v[150:151], v[190:191] op_sel_hi:[0,1,1]
	v_mov_b32_e32 v140, v143
	v_pk_mul_f32 v[140:141], v[140:141], v[148:149] op_sel:[0,1] op_sel_hi:[0,0]
	v_pk_fma_f32 v[190:191], v[142:143], v[148:149], v[140:141] op_sel_hi:[0,1,1] neg_lo:[0,0,1] neg_hi:[0,0,1]
	v_pk_fma_f32 v[148:149], v[142:143], v[148:149], v[140:141] op_sel_hi:[0,1,1]
	v_lshlrev_b64 v[140:141], 10, v[160:161]
	v_lshl_add_u64 v[140:141], s[94:95], 0, v[140:141]
	v_lshl_add_u64 v[160:161], v[140:141], 0, v[188:189]
	v_add_co_u32_e64 v160, s[0:1], s47, v160
	v_cvt_pk_bf16_f32 v140, v154, v145
	v_cvt_pk_bf16_f32 v141, v152, v147
	v_cvt_pk_bf16_f32 v142, v196, v151
	v_cvt_pk_bf16_f32 v143, v190, v149
	v_addc_co_u32_e64 v161, s[0:1], 0, v161, s[0:1]
	global_store_dwordx4 v[160:161], v[140:143], off offset:3072
	s_add_i32 s0, s3, 0xffffc020
	s_lshr_b32 s0, s0, 4
	v_add_u32_e32 v140, 0x80, v163
	v_cndmask_b32_e64 v140, v244, v140, s[40:41]
	v_and_b32_e32 v142, 0x7f, v140
	v_bitop3_b32 v143, v140, s44, v140 bitop3:0xc
	v_cvt_f32_ubyte0_e32 v142, v142
	v_mov_b32_e32 v141, s0
	v_cvt_f32_ubyte0_e32 v143, v143
	v_mul_f32_e64 v142, v142, -v214
	v_cndmask_b32_e64 v141, v141, v194, s[40:41]
	v_mul_f32_e64 v143, v143, -v212
	v_mul_f32_e32 v142, 0x3fb8aa3b, v142
	v_mul_f32_e32 v143, 0x3fb8aa3b, v143
	v_exp_f32_e32 v148, v142
	v_lshl_or_b32 v142, v141, 3, s2
	v_exp_f32_e32 v146, v143
	v_ashrrev_i32_e32 v143, 31, v142
	v_lshlrev_b64 v[142:143], 6, v[142:143]
	v_or_b32_e32 v144, v142, v216
	v_mov_b32_e32 v141, v3
	v_mad_u64_u32 v[160:161], s[0:1], v144, s45, v[140:141]
	v_mad_i32_i24 v161, v143, s45, v161
	v_lshlrev_b64 v[160:161], 1, v[160:161]
	v_mul_f32_e32 v144, v146, v154
	v_lshl_add_u64 v[162:163], s[16:17], 0, v[160:161]
	v_cvt_pk_bf16_f32 v144, v144, s0
	global_store_short v[162:163], v144, off
	v_mul_f32_e32 v144, v148, v154
	v_lshl_add_u64 v[160:161], s[4:5], 0, v[160:161]
	v_cvt_pk_bf16_f32 v144, v144, s0
	global_store_short v[160:161], v144, off
	v_mul_f32_e32 v144, v146, v145
	v_cvt_pk_bf16_f32 v144, v144, s0
	v_add_co_u32_e64 v154, s[0:1], s36, v162
	v_or_b32_e32 v142, v142, v193
	s_nop 0
	v_addc_co_u32_e64 v155, s[0:1], 0, v163, s[0:1]
	global_store_short v[154:155], v144, off offset:256
	v_mul_f32_e32 v144, v148, v145
	v_cvt_pk_bf16_f32 v150, v144, s0
	v_add_co_u32_e64 v144, s[0:1], s36, v160
	s_nop 1
	v_addc_co_u32_e64 v145, s[0:1], 0, v161, s[0:1]
	global_store_short v[144:145], v150, off offset:256
	v_mul_f32_e32 v144, v146, v152
	v_cvt_pk_bf16_f32 v150, v144, s0
	v_add_co_u32_e64 v144, s[0:1], s21, v162
	s_nop 1
	v_addc_co_u32_e64 v145, s[0:1], 0, v163, s[0:1]
	global_store_short v[144:145], v150, off offset:512
	v_mul_f32_e32 v144, v148, v152
	v_cvt_pk_bf16_f32 v150, v144, s0
	v_add_co_u32_e64 v144, s[0:1], s21, v160
	s_nop 1
	v_addc_co_u32_e64 v145, s[0:1], 0, v161, s[0:1]
	global_store_short v[144:145], v150, off offset:512
	v_mul_f32_e32 v144, v146, v147
	v_cvt_pk_bf16_f32 v150, v144, s0
	v_add_co_u32_e64 v144, s[0:1], s37, v162
	s_nop 1
	v_addc_co_u32_e64 v145, s[0:1], 0, v163, s[0:1]
	global_store_short v[144:145], v150, off offset:768
	v_mul_f32_e32 v144, v148, v147
	v_cvt_pk_bf16_f32 v147, v144, s0
	v_add_co_u32_e64 v144, s[0:1], s37, v160
	s_nop 1
	v_addc_co_u32_e64 v145, s[0:1], 0, v161, s[0:1]
	v_mad_u64_u32 v[140:141], s[0:1], v142, s45, v[140:141]
	v_mad_i32_i24 v141, v143, s45, v141
	global_store_short v[144:145], v147, off offset:768
	v_lshlrev_b64 v[140:141], 1, v[140:141]
	v_mul_f32_e32 v144, v146, v196
	v_lshl_add_u64 v[142:143], s[16:17], 0, v[140:141]
	v_cvt_pk_bf16_f32 v144, v144, s0
	global_store_short v[142:143], v144, off
	v_mul_f32_e32 v144, v148, v196
	v_lshl_add_u64 v[140:141], s[4:5], 0, v[140:141]
	v_cvt_pk_bf16_f32 v144, v144, s0
	global_store_short v[140:141], v144, off
	v_mul_f32_e32 v144, v146, v151
	v_cvt_pk_bf16_f32 v147, v144, s0
	v_add_co_u32_e64 v144, s[0:1], s36, v142
	s_nop 1
	v_addc_co_u32_e64 v145, s[0:1], 0, v143, s[0:1]
	global_store_short v[144:145], v147, off offset:256
	v_mul_f32_e32 v144, v148, v151
	v_cvt_pk_bf16_f32 v147, v144, s0
	v_add_co_u32_e64 v144, s[0:1], s36, v140
	s_nop 1
	v_addc_co_u32_e64 v145, s[0:1], 0, v141, s[0:1]
	global_store_short v[144:145], v147, off offset:256
	v_mul_f32_e32 v144, v146, v190
	v_cvt_pk_bf16_f32 v147, v144, s0
	v_add_co_u32_e64 v144, s[0:1], s21, v142
	s_nop 1
	v_addc_co_u32_e64 v145, s[0:1], 0, v143, s[0:1]
	global_store_short v[144:145], v147, off offset:512
	v_mul_f32_e32 v144, v148, v190
	v_cvt_pk_bf16_f32 v147, v144, s0
	v_add_co_u32_e64 v144, s[0:1], s21, v140
	s_nop 1
	v_addc_co_u32_e64 v145, s[0:1], 0, v141, s[0:1]
	global_store_short v[144:145], v147, off offset:512
	v_mul_f32_e32 v144, v146, v149
	v_cvt_pk_bf16_f32 v144, v144, s0
	v_add_co_u32_e64 v142, s[0:1], s37, v142
	s_nop 1
	v_addc_co_u32_e64 v143, s[0:1], 0, v143, s[0:1]
	global_store_short v[142:143], v144, off offset:768
	v_mul_f32_e32 v142, v148, v149
	v_cvt_pk_bf16_f32 v142, v142, s0
	v_add_co_u32_e64 v140, s[0:1], s37, v140
	s_nop 1
	v_addc_co_u32_e64 v141, s[0:1], 0, v141, s[0:1]
	global_store_short v[140:141], v142, off offset:768
	v_pk_mul_f32 v[142:143], v[104:105], v[158:159] op_sel_hi:[1,0]
	v_pk_mul_f32 v[140:141], v[106:107], v[158:159] op_sel_hi:[1,0]
	v_pk_mul_f32 v[144:145], v[136:137], v[142:143] op_sel:[1,1] op_sel_hi:[1,0]
	s_nop 0
	v_pk_fma_f32 v[146:147], v[136:137], v[142:143], v[144:145] op_sel_hi:[0,1,1] neg_lo:[0,0,1] neg_hi:[0,0,1]
	v_pk_fma_f32 v[136:137], v[136:137], v[142:143], v[144:145] op_sel_hi:[0,1,1]
	v_mov_b32_e32 v136, v139
	v_pk_mul_f32 v[142:143], v[136:137], v[140:141] op_sel:[0,1] op_sel_hi:[0,0]
	v_pk_fma_f32 v[144:145], v[138:139], v[140:141], v[142:143] op_sel_hi:[0,1,1] neg_lo:[0,0,1] neg_hi:[0,0,1]
	v_pk_fma_f32 v[138:139], v[138:139], v[140:141], v[142:143] op_sel_hi:[0,1,1]
	v_pk_mul_f32 v[142:143], v[100:101], v[158:159] op_sel_hi:[1,0]
	v_pk_mul_f32 v[140:141], v[102:103], v[158:159] op_sel_hi:[1,0]
	v_pk_mul_f32 v[148:149], v[132:133], v[142:143] op_sel:[1,1] op_sel_hi:[1,0]
	s_nop 0
	v_pk_fma_f32 v[150:151], v[132:133], v[142:143], v[148:149] op_sel_hi:[0,1,1] neg_lo:[0,0,1] neg_hi:[0,0,1]
	v_pk_fma_f32 v[142:143], v[132:133], v[142:143], v[148:149] op_sel_hi:[0,1,1]
	v_mov_b32_e32 v132, v135
	v_pk_mul_f32 v[132:133], v[132:133], v[140:141] op_sel:[0,1] op_sel_hi:[0,0]
	v_pk_fma_f32 v[148:149], v[134:135], v[140:141], v[132:133] op_sel_hi:[0,1,1] neg_lo:[0,0,1] neg_hi:[0,0,1]
	v_pk_fma_f32 v[140:141], v[134:135], v[140:141], v[132:133] op_sel_hi:[0,1,1]
	v_lshlrev_b64 v[132:133], 10, v[156:157]
	v_lshl_add_u64 v[132:133], s[94:95], 0, v[132:133]
	v_lshl_add_u64 v[152:153], v[132:133], 0, v[188:189]
	v_add_co_u32_e64 v152, s[0:1], s47, v152
	v_cvt_pk_bf16_f32 v132, v146, v137
	v_cvt_pk_bf16_f32 v133, v144, v139
	v_cvt_pk_bf16_f32 v134, v150, v143
	v_cvt_pk_bf16_f32 v135, v148, v141
	v_addc_co_u32_e64 v153, s[0:1], 0, v153, s[0:1]
	global_store_dwordx4 v[152:153], v[132:135], off offset:3072
	s_add_i32 s0, s3, 0xffffc030
	s_lshr_b32 s0, s0, 4
	v_add_u32_e32 v132, 0x80, v159
	v_cndmask_b32_e32 v132, v244, v132, vcc
	v_and_b32_e32 v134, 0x7f, v132
	v_bitop3_b32 v135, v132, s44, v132 bitop3:0xc
	v_cvt_f32_ubyte0_e32 v134, v134
	v_mov_b32_e32 v133, s0
	v_cvt_f32_ubyte0_e32 v135, v135
	v_mul_f32_e64 v134, v134, -v214
	v_cndmask_b32_e32 v133, v133, v194, vcc
	v_mul_f32_e64 v135, v135, -v212
	v_mul_f32_e32 v134, 0x3fb8aa3b, v134
	v_mul_f32_e32 v135, 0x3fb8aa3b, v135
	v_exp_f32_e32 v140, v134
	v_lshl_or_b32 v134, v133, 3, s2
	v_exp_f32_e32 v138, v135
	v_ashrrev_i32_e32 v135, 31, v134
	v_lshlrev_b64 v[134:135], 6, v[134:135]
	v_or_b32_e32 v136, v134, v216
	v_mov_b32_e32 v133, v3
	v_mad_u64_u32 v[152:153], s[0:1], v136, s45, v[132:133]
	v_mad_i32_i24 v153, v135, s45, v153
	v_lshlrev_b64 v[152:153], 1, v[152:153]
	v_mul_f32_e32 v136, v138, v146
	v_lshl_add_u64 v[154:155], s[16:17], 0, v[152:153]
	v_cvt_pk_bf16_f32 v136, v136, s0
	global_store_short v[154:155], v136, off
	v_mul_f32_e32 v136, v140, v146
	v_lshl_add_u64 v[152:153], s[4:5], 0, v[152:153]
	v_cvt_pk_bf16_f32 v136, v136, s0
	global_store_short v[152:153], v136, off
	v_mul_f32_e32 v136, v138, v137
	v_add_co_u32_e32 v146, vcc, s36, v154
	v_cvt_pk_bf16_f32 v136, v136, s0
	s_nop 0
	v_addc_co_u32_e32 v147, vcc, 0, v155, vcc
	global_store_short v[146:147], v136, off offset:256
	v_mul_f32_e32 v136, v140, v137
	v_cvt_pk_bf16_f32 v142, v136, s0
	v_add_co_u32_e32 v136, vcc, s36, v152
	v_or_b32_e32 v134, v134, v193
	s_nop 0
	v_addc_co_u32_e32 v137, vcc, 0, v153, vcc
	global_store_short v[136:137], v142, off offset:256
	v_mul_f32_e32 v136, v138, v144
	v_cvt_pk_bf16_f32 v142, v136, s0
	v_add_co_u32_e32 v136, vcc, s21, v154
	s_cmp_eq_u32 s48, 64
	s_nop 0
	v_addc_co_u32_e32 v137, vcc, 0, v155, vcc
	global_store_short v[136:137], v142, off offset:512
	v_mul_f32_e32 v136, v140, v144
	v_cvt_pk_bf16_f32 v142, v136, s0
	v_add_co_u32_e32 v136, vcc, s21, v152
	s_nop 1
	v_addc_co_u32_e32 v137, vcc, 0, v153, vcc
	global_store_short v[136:137], v142, off offset:512
	v_mul_f32_e32 v136, v138, v139
	v_cvt_pk_bf16_f32 v142, v136, s0
	v_add_co_u32_e32 v136, vcc, s37, v154
	s_nop 1
	v_addc_co_u32_e32 v137, vcc, 0, v155, vcc
	global_store_short v[136:137], v142, off offset:768
	v_mul_f32_e32 v136, v140, v139
	v_cvt_pk_bf16_f32 v139, v136, s0
	v_add_co_u32_e32 v136, vcc, s37, v152
	v_mad_u64_u32 v[132:133], s[0:1], v134, s45, v[132:133]
	s_nop 0
	v_addc_co_u32_e32 v137, vcc, 0, v153, vcc
	v_mad_i32_i24 v133, v135, s45, v133
	global_store_short v[136:137], v139, off offset:768
	v_lshlrev_b64 v[132:133], 1, v[132:133]
	v_mul_f32_e32 v136, v138, v150
	v_lshl_add_u64 v[134:135], s[16:17], 0, v[132:133]
	v_cvt_pk_bf16_f32 v136, v136, s0
	global_store_short v[134:135], v136, off
	v_mul_f32_e32 v136, v140, v150
	v_lshl_add_u64 v[132:133], s[4:5], 0, v[132:133]
	v_cvt_pk_bf16_f32 v136, v136, s0
	global_store_short v[132:133], v136, off
	v_mul_f32_e32 v136, v138, v143
	v_cvt_pk_bf16_f32 v139, v136, s0
	v_add_co_u32_e32 v136, vcc, s36, v134
	s_nop 1
	v_addc_co_u32_e32 v137, vcc, 0, v135, vcc
	global_store_short v[136:137], v139, off offset:256
	v_mul_f32_e32 v136, v140, v143
	v_cvt_pk_bf16_f32 v139, v136, s0
	v_add_co_u32_e32 v136, vcc, s36, v132
	s_nop 1
	v_addc_co_u32_e32 v137, vcc, 0, v133, vcc
	global_store_short v[136:137], v139, off offset:256
	v_mul_f32_e32 v136, v138, v148
	v_cvt_pk_bf16_f32 v139, v136, s0
	v_add_co_u32_e32 v136, vcc, s21, v134
	s_nop 1
	v_addc_co_u32_e32 v137, vcc, 0, v135, vcc
	global_store_short v[136:137], v139, off offset:512
	v_mul_f32_e32 v136, v140, v148
	v_cvt_pk_bf16_f32 v139, v136, s0
	v_add_co_u32_e32 v136, vcc, s21, v132
	s_nop 1
	v_addc_co_u32_e32 v137, vcc, 0, v133, vcc
	global_store_short v[136:137], v139, off offset:512
	v_mul_f32_e32 v136, v138, v141
	v_add_co_u32_e32 v134, vcc, 0x3000, v134
	v_cvt_pk_bf16_f32 v136, v136, s0
	s_nop 0
	v_addc_co_u32_e32 v135, vcc, 0, v135, vcc
	global_store_short v[134:135], v136, off offset:768
	v_mul_f32_e32 v134, v140, v141
	v_add_co_u32_e32 v132, vcc, 0x3000, v132
	v_cvt_pk_bf16_f32 v134, v134, s0
	s_nop 0
	v_addc_co_u32_e32 v133, vcc, 0, v133, vcc
	global_store_short v[132:133], v134, off offset:768
	s_cbranch_scc1 .LBB0_162
	s_add_i32 s0, s3, 0x80
	v_or_b32_e32 v134, s0, v181
	v_bitop3_b32 v138, s0, v250, v181 bitop3:0xc8
	v_or_b32_e32 v136, 16, v138
	v_cmp_gt_i32_e64 s[42:43], s20, v134
	v_readlane_b32 s4, v251, 9
	v_ashrrev_i32_e32 v135, 31, v134
	v_cndmask_b32_e64 v136, v181, v136, s[42:43]
	v_lshlrev_b32_e32 v136, 8, v136
	v_mov_b32_e32 v137, v3
	v_readlane_b32 s5, v251, 10
	v_lshl_add_u64 v[132:133], v[134:135], 2, s[70:71]
	global_load_dword v198, v[132:133], off
	v_lshl_add_u64 v[136:137], s[4:5], 0, v[136:137]
	v_lshl_add_u64 v[136:137], v[136:137], 0, v[2:3]
	global_load_dwordx4 v[144:147], v[136:137], off
	global_load_dwordx4 v[140:143], v[136:137], off offset:16
	s_movk_i32 s16, 0x7df
	v_bitop3_b32 v168, v134, s16, 16 bitop3:0xc8
	s_movk_i32 s16, 0x7ef
	s_add_i32 s1, s3, 0xffffc080
	v_bitop3_b32 v203, v134, s16, 32 bitop3:0xc8
	s_movk_i32 s16, 0x7ff
	s_ashr_i32 s0, s0, 11
	s_lshr_b32 s1, s1, 4
	v_or_b32_e32 v200, 16, v134
	v_or_b32_e32 v194, 32, v134
	v_or_b32_e32 v190, 48, v134
	v_bitop3_b32 v197, v134, s16, 48 bitop3:0xc8
	v_add_u32_e32 v150, 0x80, v138
	v_mov_b32_e32 v136, s1
	v_mov_b32_e32 v199, s0
	v_add_u32_e32 v138, 16, v168
	v_or_b32_e32 v148, 16, v203
	v_add_u32_e32 v151, 16, v197
	v_lshlrev_b64 v[134:135], 10, v[134:135]
	v_cmp_gt_i32_e64 s[44:45], s20, v200
	v_cmp_gt_i32_e64 s[40:41], s20, v194
	v_cmp_gt_i32_e32 vcc, s20, v190
	v_cndmask_b32_e64 v169, v136, v199, s[42:43]
	v_cndmask_b32_e64 v136, v181, v138, s[44:45]
	v_cndmask_b32_e64 v138, v181, v148, s[40:41]
	global_load_dword v202, v[132:133], off offset:64
	global_load_dword v196, v[132:133], off offset:128
	global_load_dword v192, v[132:133], off offset:192
	v_cndmask_b32_e32 v148, v181, v151, vcc
	v_lshl_add_u64 v[132:133], s[94:95], 0, v[134:135]
	v_mov_b32_e32 v137, v3
	v_mov_b32_e32 v139, v3
	v_mov_b32_e32 v149, v3
	v_lshlrev_b32_e32 v136, 8, v136
	v_lshlrev_b32_e32 v138, 8, v138
	v_lshlrev_b32_e32 v148, 8, v148
	v_lshl_add_u64 v[132:133], v[132:133], 0, v[188:189]
	v_lshl_add_u64 v[134:135], s[4:5], 0, v[136:137]
	v_lshl_add_u64 v[136:137], s[4:5], 0, v[138:139]
	v_lshl_add_u64 v[138:139], s[4:5], 0, v[148:149]
	v_add_co_u32_e64 v204, s[0:1], s47, v132
	v_readlane_b32 s16, v251, 7
	s_nop 0
	v_addc_co_u32_e64 v205, s[0:1], 0, v133, s[0:1]
	v_lshl_add_u64 v[132:133], v[134:135], 0, v[2:3]
	v_lshl_add_u64 v[134:135], v[136:137], 0, v[2:3]
	v_lshl_add_u64 v[136:137], v[138:139], 0, v[2:3]
	v_cndmask_b32_e64 v2, v244, v150, s[42:43]
	global_load_dwordx4 v[156:159], v[132:133], off offset:16
	global_load_dwordx4 v[160:163], v[132:133], off
	global_load_dwordx4 v[148:151], v[134:135], off offset:16
	global_load_dwordx4 v[152:155], v[134:135], off
	s_nop 0
	global_load_dwordx4 v[132:135], v[136:137], off offset:16
	s_nop 0
	global_load_dwordx4 v[136:139], v[136:137], off
	s_movk_i32 s42, 0x7f
	s_movk_i32 s43, 0x880
	v_readlane_b32 s17, v251, 8
	v_readlane_b32 s4, v251, 5
	v_readlane_b32 s5, v251, 6
	v_ashrrev_i32_e32 v201, 31, v200
	v_ashrrev_i32_e32 v195, 31, v194
	v_ashrrev_i32_e32 v191, 31, v190
	s_waitcnt vmcnt(0)
	v_pk_mul_f32 v[208:209], v[96:97], v[198:199] op_sel_hi:[1,0]
	v_pk_mul_f32 v[220:221], v[92:93], v[198:199] op_sel_hi:[1,0]
	v_pk_mul_f32 v[206:207], v[98:99], v[198:199] op_sel_hi:[1,0]
	v_pk_mul_f32 v[210:211], v[94:95], v[198:199] op_sel_hi:[1,0]
	v_pk_mul_f32 v[222:223], v[144:145], v[208:209] op_sel:[1,1] op_sel_hi:[1,0]
	v_mov_b32_e32 v198, v147
	v_pk_mul_f32 v[234:235], v[140:141], v[220:221] op_sel:[1,1] op_sel_hi:[1,0]
	v_mov_b32_e32 v218, v143
	v_pk_fma_f32 v[236:237], v[144:145], v[208:209], v[222:223] op_sel_hi:[0,1,1] neg_lo:[0,0,1] neg_hi:[0,0,1]
	v_pk_fma_f32 v[144:145], v[144:145], v[208:209], v[222:223] op_sel_hi:[0,1,1]
	v_pk_mul_f32 v[208:209], v[198:199], v[206:207] op_sel:[0,1] op_sel_hi:[0,0]
	v_pk_fma_f32 v[222:223], v[140:141], v[220:221], v[234:235] op_sel_hi:[0,1,1] neg_lo:[0,0,1] neg_hi:[0,0,1]
	v_pk_fma_f32 v[220:221], v[140:141], v[220:221], v[234:235] op_sel_hi:[0,1,1]
	v_pk_mul_f32 v[140:141], v[218:219], v[210:211] op_sel:[0,1] op_sel_hi:[0,0]
	v_pk_fma_f32 v[234:235], v[146:147], v[206:207], v[208:209] op_sel_hi:[0,1,1] neg_lo:[0,0,1] neg_hi:[0,0,1]
	v_pk_fma_f32 v[146:147], v[146:147], v[206:207], v[208:209] op_sel_hi:[0,1,1]
	v_pk_fma_f32 v[206:207], v[142:143], v[210:211], v[140:141] op_sel_hi:[0,1,1] neg_lo:[0,0,1] neg_hi:[0,0,1]
	v_pk_fma_f32 v[208:209], v[142:143], v[210:211], v[140:141] op_sel_hi:[0,1,1]
	v_cvt_pk_bf16_f32 v140, v236, v145
	v_cvt_pk_bf16_f32 v142, v222, v221
	v_cvt_pk_bf16_f32 v141, v234, v147
	v_cvt_pk_bf16_f32 v143, v206, v209
	global_store_dwordx4 v[204:205], v[140:143], off offset:3072
	s_nop 1
	v_and_b32_e32 v140, 0x7f, v2
	v_bitop3_b32 v141, v2, s42, v2 bitop3:0xc
	v_cvt_f32_ubyte0_e32 v140, v140
	v_cvt_f32_ubyte0_e32 v141, v141
	v_mul_f32_e64 v140, v140, -v214
	v_mul_f32_e64 v141, v141, -v212
	v_mul_f32_e32 v140, 0x3fb8aa3b, v140
	v_mul_f32_e32 v141, 0x3fb8aa3b, v141
	v_exp_f32_e32 v198, v140
	v_lshl_or_b32 v140, v169, 3, s2
	v_exp_f32_e32 v146, v141
	v_ashrrev_i32_e32 v141, 31, v140
	v_lshlrev_b64 v[140:141], 6, v[140:141]
	v_or_b32_e32 v142, v140, v216
	v_mad_u64_u32 v[142:143], s[0:1], v142, s43, v[2:3]
	v_mad_i32_i24 v143, v141, s43, v143
	v_lshlrev_b64 v[142:143], 1, v[142:143]
	v_mul_f32_e32 v144, v146, v236
	v_lshl_add_u64 v[204:205], s[16:17], 0, v[142:143]
	v_cvt_pk_bf16_f32 v144, v144, s0
	global_store_short v[204:205], v144, off
	v_mul_f32_e32 v144, v198, v236
	v_lshl_add_u64 v[142:143], s[4:5], 0, v[142:143]
	v_cvt_pk_bf16_f32 v144, v144, s0
	global_store_short v[142:143], v144, off
	v_mul_f32_e32 v144, v146, v145
	v_cvt_pk_bf16_f32 v144, v144, s0
	v_add_co_u32_e64 v210, s[0:1], s36, v204
	v_or_b32_e32 v140, v140, v193
	s_nop 0
	v_addc_co_u32_e64 v211, s[0:1], 0, v205, s[0:1]
	global_store_short v[210:211], v144, off offset:256
	v_mul_f32_e32 v144, v198, v145
	v_cvt_pk_bf16_f32 v169, v144, s0
	v_add_co_u32_e64 v144, s[0:1], s36, v142
	s_nop 1
	v_addc_co_u32_e64 v145, s[0:1], 0, v143, s[0:1]
	global_store_short v[144:145], v169, off offset:256
	v_mul_f32_e32 v144, v146, v234
	v_cvt_pk_bf16_f32 v169, v144, s0
	v_add_co_u32_e64 v144, s[0:1], s21, v204
	s_nop 1
	v_addc_co_u32_e64 v145, s[0:1], 0, v205, s[0:1]
	global_store_short v[144:145], v169, off offset:512
	v_mul_f32_e32 v144, v198, v234
	v_cvt_pk_bf16_f32 v169, v144, s0
	v_add_co_u32_e64 v144, s[0:1], s21, v142
	s_nop 1
	v_addc_co_u32_e64 v145, s[0:1], 0, v143, s[0:1]
	global_store_short v[144:145], v169, off offset:512
	v_mul_f32_e32 v144, v146, v147
	v_cvt_pk_bf16_f32 v169, v144, s0
	v_add_co_u32_e64 v144, s[0:1], s37, v204
	s_nop 1
	v_addc_co_u32_e64 v145, s[0:1], 0, v205, s[0:1]
	global_store_short v[144:145], v169, off offset:768
	v_mul_f32_e32 v144, v198, v147
	v_cvt_pk_bf16_f32 v144, v144, s0
	v_add_co_u32_e64 v142, s[0:1], s37, v142
	s_nop 1
	v_addc_co_u32_e64 v143, s[0:1], 0, v143, s[0:1]
	global_store_short v[142:143], v144, off offset:768
	v_mad_u64_u32 v[142:143], s[0:1], v140, s43, v[2:3]
	v_mad_i32_i24 v143, v141, s43, v143
	v_lshlrev_b64 v[140:141], 1, v[142:143]
	v_mul_f32_e32 v2, v146, v222
	v_lshl_add_u64 v[142:143], s[16:17], 0, v[140:141]
	v_cvt_pk_bf16_f32 v2, v2, s0
	global_store_short v[142:143], v2, off
	v_mul_f32_e32 v2, v198, v222
	v_lshl_add_u64 v[140:141], s[4:5], 0, v[140:141]
	v_cvt_pk_bf16_f32 v2, v2, s0
	global_store_short v[140:141], v2, off
	v_mul_f32_e32 v2, v146, v221
	v_cvt_pk_bf16_f32 v2, v2, s0
	v_add_co_u32_e64 v144, s[0:1], s36, v142
	s_nop 1
	v_addc_co_u32_e64 v145, s[0:1], 0, v143, s[0:1]
	global_store_short v[144:145], v2, off offset:256
	v_mul_f32_e32 v2, v198, v221
	v_cvt_pk_bf16_f32 v2, v2, s0
	v_add_co_u32_e64 v144, s[0:1], s36, v140
	s_nop 1
	v_addc_co_u32_e64 v145, s[0:1], 0, v141, s[0:1]
	global_store_short v[144:145], v2, off offset:256
	v_mul_f32_e32 v2, v146, v206
	v_cvt_pk_bf16_f32 v2, v2, s0
	v_add_co_u32_e64 v144, s[0:1], s21, v142
	s_nop 1
	v_addc_co_u32_e64 v145, s[0:1], 0, v143, s[0:1]
	global_store_short v[144:145], v2, off offset:512
	v_mul_f32_e32 v2, v198, v206
	v_cvt_pk_bf16_f32 v2, v2, s0
	v_add_co_u32_e64 v144, s[0:1], s21, v140
	s_nop 1
	v_addc_co_u32_e64 v145, s[0:1], 0, v141, s[0:1]
	global_store_short v[144:145], v2, off offset:512
	v_mul_f32_e32 v2, v146, v209
	v_cvt_pk_bf16_f32 v2, v2, s0
	v_add_co_u32_e64 v142, s[0:1], s37, v142
	s_nop 1
	v_addc_co_u32_e64 v143, s[0:1], 0, v143, s[0:1]
	global_store_short v[142:143], v2, off offset:768
	v_mul_f32_e32 v2, v198, v209
	v_cvt_pk_bf16_f32 v2, v2, s0
	v_add_co_u32_e64 v140, s[0:1], s37, v140
	v_pk_mul_f32 v[142:143], v[88:89], v[202:203] op_sel_hi:[1,0]
	s_nop 0
	v_addc_co_u32_e64 v141, s[0:1], 0, v141, s[0:1]
	global_store_short v[140:141], v2, off offset:768
	v_pk_mul_f32 v[140:141], v[90:91], v[202:203] op_sel_hi:[1,0]
	v_pk_mul_f32 v[144:145], v[160:161], v[142:143] op_sel:[1,1] op_sel_hi:[1,0]
	v_mov_b32_e32 v2, v163
	v_pk_fma_f32 v[146:147], v[160:161], v[142:143], v[144:145] op_sel_hi:[0,1,1] neg_lo:[0,0,1] neg_hi:[0,0,1]
	v_pk_fma_f32 v[144:145], v[160:161], v[142:143], v[144:145] op_sel_hi:[0,1,1]
	v_pk_mul_f32 v[142:143], v[2:3], v[140:141] op_sel:[0,1] op_sel_hi:[0,0]
	v_pk_fma_f32 v[160:161], v[162:163], v[140:141], v[142:143] op_sel_hi:[0,1,1] neg_lo:[0,0,1] neg_hi:[0,0,1]
	v_pk_fma_f32 v[162:163], v[162:163], v[140:141], v[142:143] op_sel_hi:[0,1,1]
	v_pk_mul_f32 v[142:143], v[84:85], v[202:203] op_sel_hi:[1,0]
	v_pk_mul_f32 v[140:141], v[86:87], v[202:203] op_sel_hi:[1,0]
	v_pk_mul_f32 v[204:205], v[156:157], v[142:143] op_sel:[1,1] op_sel_hi:[1,0]
	v_mov_b32_e32 v2, v159
	v_pk_fma_f32 v[206:207], v[156:157], v[142:143], v[204:205] op_sel_hi:[0,1,1] neg_lo:[0,0,1] neg_hi:[0,0,1]
	v_pk_fma_f32 v[156:157], v[156:157], v[142:143], v[204:205] op_sel_hi:[0,1,1]
	v_pk_mul_f32 v[142:143], v[2:3], v[140:141] op_sel:[0,1] op_sel_hi:[0,0]
	v_pk_fma_f32 v[204:205], v[158:159], v[140:141], v[142:143] op_sel_hi:[0,1,1] neg_lo:[0,0,1] neg_hi:[0,0,1]
	v_pk_fma_f32 v[158:159], v[158:159], v[140:141], v[142:143] op_sel_hi:[0,1,1]
	v_lshlrev_b64 v[140:141], 10, v[200:201]
	v_lshl_add_u64 v[140:141], s[94:95], 0, v[140:141]
	v_lshl_add_u64 v[200:201], v[140:141], 0, v[188:189]
	v_add_co_u32_e64 v200, s[0:1], s47, v200
	v_add_u32_e32 v2, 0x80, v168
	s_nop 0
	v_addc_co_u32_e64 v201, s[0:1], 0, v201, s[0:1]
	v_cvt_pk_bf16_f32 v140, v146, v145
	v_cvt_pk_bf16_f32 v141, v160, v163
	v_cvt_pk_bf16_f32 v142, v206, v157
	v_cvt_pk_bf16_f32 v143, v204, v159
	s_add_i32 s0, s3, 0xffffc090
	v_cndmask_b32_e64 v2, v244, v2, s[44:45]
	global_store_dwordx4 v[200:201], v[140:143], off offset:3072
	s_lshr_b32 s0, s0, 4
	s_nop 0
	v_and_b32_e32 v141, 0x7f, v2
	v_mov_b32_e32 v140, s0
	v_bitop3_b32 v142, v2, s42, v2 bitop3:0xc
	v_cvt_f32_ubyte0_e32 v141, v141
	v_cndmask_b32_e64 v140, v140, v199, s[44:45]
	v_cvt_f32_ubyte0_e32 v142, v142
	v_mul_f32_e64 v141, v141, -v214
	v_mul_f32_e64 v142, v142, -v212
	v_mul_f32_e32 v141, 0x3fb8aa3b, v141
	v_lshl_or_b32 v140, v140, 3, s2
	v_mul_f32_e32 v142, 0x3fb8aa3b, v142
	v_exp_f32_e32 v158, v141
	v_ashrrev_i32_e32 v141, 31, v140
	v_exp_f32_e32 v156, v142
	v_lshlrev_b64 v[140:141], 6, v[140:141]
	v_or_b32_e32 v142, v140, v216
	v_mad_u64_u32 v[142:143], s[0:1], v142, s43, v[2:3]
	v_mad_i32_i24 v143, v141, s43, v143
	v_lshlrev_b64 v[142:143], 1, v[142:143]
	v_mul_f32_e32 v144, v156, v146
	v_lshl_add_u64 v[200:201], s[16:17], 0, v[142:143]
	v_cvt_pk_bf16_f32 v144, v144, s0
	global_store_short v[200:201], v144, off
	v_mul_f32_e32 v144, v158, v146
	v_lshl_add_u64 v[142:143], s[4:5], 0, v[142:143]
	v_cvt_pk_bf16_f32 v144, v144, s0
	global_store_short v[142:143], v144, off
	v_mul_f32_e32 v144, v156, v145
	v_cvt_pk_bf16_f32 v144, v144, s0
	v_add_co_u32_e64 v146, s[0:1], s36, v200
	v_or_b32_e32 v140, v140, v193
	s_nop 0
	v_addc_co_u32_e64 v147, s[0:1], 0, v201, s[0:1]
	global_store_short v[146:147], v144, off offset:256
	v_mul_f32_e32 v144, v158, v145
	v_cvt_pk_bf16_f32 v146, v144, s0
	v_add_co_u32_e64 v144, s[0:1], s36, v142
	s_nop 1
	v_addc_co_u32_e64 v145, s[0:1], 0, v143, s[0:1]
	global_store_short v[144:145], v146, off offset:256
	v_mul_f32_e32 v144, v156, v160
	v_cvt_pk_bf16_f32 v146, v144, s0
	v_add_co_u32_e64 v144, s[0:1], s21, v200
	s_nop 1
	v_addc_co_u32_e64 v145, s[0:1], 0, v201, s[0:1]
	global_store_short v[144:145], v146, off offset:512
	v_mul_f32_e32 v144, v158, v160
	v_cvt_pk_bf16_f32 v146, v144, s0
	v_add_co_u32_e64 v144, s[0:1], s21, v142
	s_nop 1
	v_addc_co_u32_e64 v145, s[0:1], 0, v143, s[0:1]
	global_store_short v[144:145], v146, off offset:512
	v_mul_f32_e32 v144, v156, v163
	v_cvt_pk_bf16_f32 v146, v144, s0
	v_add_co_u32_e64 v144, s[0:1], s37, v200
	s_nop 1
	v_addc_co_u32_e64 v145, s[0:1], 0, v201, s[0:1]
	global_store_short v[144:145], v146, off offset:768
	v_mul_f32_e32 v144, v158, v163
	v_cvt_pk_bf16_f32 v144, v144, s0
	v_add_co_u32_e64 v142, s[0:1], s37, v142
	s_nop 1
	v_addc_co_u32_e64 v143, s[0:1], 0, v143, s[0:1]
	global_store_short v[142:143], v144, off offset:768
	v_mad_u64_u32 v[142:143], s[0:1], v140, s43, v[2:3]
	v_mad_i32_i24 v143, v141, s43, v143
	v_lshlrev_b64 v[140:141], 1, v[142:143]
	v_mul_f32_e32 v2, v156, v206
	v_lshl_add_u64 v[142:143], s[16:17], 0, v[140:141]
	v_cvt_pk_bf16_f32 v2, v2, s0
	global_store_short v[142:143], v2, off
	v_mul_f32_e32 v2, v158, v206
	v_lshl_add_u64 v[140:141], s[4:5], 0, v[140:141]
	v_cvt_pk_bf16_f32 v2, v2, s0
	global_store_short v[140:141], v2, off
	v_mul_f32_e32 v2, v156, v157
	v_cvt_pk_bf16_f32 v2, v2, s0
	v_add_co_u32_e64 v144, s[0:1], s36, v142
	s_nop 1
	v_addc_co_u32_e64 v145, s[0:1], 0, v143, s[0:1]
	global_store_short v[144:145], v2, off offset:256
	v_mul_f32_e32 v2, v158, v157
	v_cvt_pk_bf16_f32 v2, v2, s0
	v_add_co_u32_e64 v144, s[0:1], s36, v140
	s_nop 1
	v_addc_co_u32_e64 v145, s[0:1], 0, v141, s[0:1]
	global_store_short v[144:145], v2, off offset:256
	v_mul_f32_e32 v2, v156, v204
	v_cvt_pk_bf16_f32 v2, v2, s0
	v_add_co_u32_e64 v144, s[0:1], s21, v142
	s_nop 1
	v_addc_co_u32_e64 v145, s[0:1], 0, v143, s[0:1]
	global_store_short v[144:145], v2, off offset:512
	v_mul_f32_e32 v2, v158, v204
	v_cvt_pk_bf16_f32 v2, v2, s0
	v_add_co_u32_e64 v144, s[0:1], s21, v140
	s_nop 1
	v_addc_co_u32_e64 v145, s[0:1], 0, v141, s[0:1]
	global_store_short v[144:145], v2, off offset:512
	v_mul_f32_e32 v2, v156, v159
	v_cvt_pk_bf16_f32 v2, v2, s0
	v_add_co_u32_e64 v142, s[0:1], s37, v142
	s_nop 1
	v_addc_co_u32_e64 v143, s[0:1], 0, v143, s[0:1]
	global_store_short v[142:143], v2, off offset:768
	v_mul_f32_e32 v2, v158, v159
	v_cvt_pk_bf16_f32 v2, v2, s0
	v_add_co_u32_e64 v140, s[0:1], s37, v140
	v_pk_mul_f32 v[142:143], v[80:81], v[196:197] op_sel_hi:[1,0]
	s_nop 0
	v_addc_co_u32_e64 v141, s[0:1], 0, v141, s[0:1]
	global_store_short v[140:141], v2, off offset:768
	v_pk_mul_f32 v[140:141], v[82:83], v[196:197] op_sel_hi:[1,0]
	v_pk_mul_f32 v[144:145], v[152:153], v[142:143] op_sel:[1,1] op_sel_hi:[1,0]
	v_mov_b32_e32 v2, v155
	v_pk_fma_f32 v[146:147], v[152:153], v[142:143], v[144:145] op_sel_hi:[0,1,1] neg_lo:[0,0,1] neg_hi:[0,0,1]
	v_pk_fma_f32 v[144:145], v[152:153], v[142:143], v[144:145] op_sel_hi:[0,1,1]
	v_pk_mul_f32 v[142:143], v[2:3], v[140:141] op_sel:[0,1] op_sel_hi:[0,0]
	v_pk_fma_f32 v[152:153], v[154:155], v[140:141], v[142:143] op_sel_hi:[0,1,1] neg_lo:[0,0,1] neg_hi:[0,0,1]
	v_pk_fma_f32 v[154:155], v[154:155], v[140:141], v[142:143] op_sel_hi:[0,1,1]
	v_pk_mul_f32 v[142:143], v[76:77], v[196:197] op_sel_hi:[1,0]
	v_pk_mul_f32 v[140:141], v[78:79], v[196:197] op_sel_hi:[1,0]
	v_pk_mul_f32 v[156:157], v[148:149], v[142:143] op_sel:[1,1] op_sel_hi:[1,0]
	v_mov_b32_e32 v2, v151
	v_pk_fma_f32 v[158:159], v[148:149], v[142:143], v[156:157] op_sel_hi:[0,1,1] neg_lo:[0,0,1] neg_hi:[0,0,1]
	v_pk_fma_f32 v[148:149], v[148:149], v[142:143], v[156:157] op_sel_hi:[0,1,1]
	v_pk_mul_f32 v[142:143], v[2:3], v[140:141] op_sel:[0,1] op_sel_hi:[0,0]
	v_pk_fma_f32 v[156:157], v[150:151], v[140:141], v[142:143] op_sel_hi:[0,1,1] neg_lo:[0,0,1] neg_hi:[0,0,1]
	v_pk_fma_f32 v[150:151], v[150:151], v[140:141], v[142:143] op_sel_hi:[0,1,1]
	v_lshlrev_b64 v[140:141], 10, v[194:195]
	v_lshl_add_u64 v[140:141], s[94:95], 0, v[140:141]
	v_lshl_add_u64 v[160:161], v[140:141], 0, v[188:189]
	v_add_co_u32_e64 v160, s[0:1], s47, v160
	v_add_u32_e32 v2, 0x80, v203
	s_nop 0
	v_addc_co_u32_e64 v161, s[0:1], 0, v161, s[0:1]
	v_cvt_pk_bf16_f32 v140, v146, v145
	v_cvt_pk_bf16_f32 v141, v152, v155
	v_cvt_pk_bf16_f32 v142, v158, v149
	v_cvt_pk_bf16_f32 v143, v156, v151
	s_add_i32 s0, s3, 0xffffc0a0
	v_cndmask_b32_e64 v2, v244, v2, s[40:41]
	global_store_dwordx4 v[160:161], v[140:143], off offset:3072
	s_lshr_b32 s0, s0, 4
	s_addk_i32 s3, 0xc0b0
	v_and_b32_e32 v141, 0x7f, v2
	v_mov_b32_e32 v140, s0
	v_bitop3_b32 v142, v2, s42, v2 bitop3:0xc
	v_cvt_f32_ubyte0_e32 v141, v141
	v_cndmask_b32_e64 v140, v140, v199, s[40:41]
	v_cvt_f32_ubyte0_e32 v142, v142
	v_mul_f32_e64 v141, v141, -v214
	v_mul_f32_e64 v142, v142, -v212
	v_mul_f32_e32 v141, 0x3fb8aa3b, v141
	v_lshl_or_b32 v140, v140, 3, s2
	v_mul_f32_e32 v142, 0x3fb8aa3b, v142
	v_exp_f32_e32 v150, v141
	v_ashrrev_i32_e32 v141, 31, v140
	v_exp_f32_e32 v148, v142
	v_lshlrev_b64 v[140:141], 6, v[140:141]
	v_or_b32_e32 v142, v140, v216
	v_mad_u64_u32 v[142:143], s[0:1], v142, s43, v[2:3]
	v_mad_i32_i24 v143, v141, s43, v143
	v_lshlrev_b64 v[142:143], 1, v[142:143]
	v_mul_f32_e32 v144, v148, v146
	v_lshl_add_u64 v[160:161], s[16:17], 0, v[142:143]
	v_cvt_pk_bf16_f32 v144, v144, s0
	global_store_short v[160:161], v144, off
	v_mul_f32_e32 v144, v150, v146
	v_lshl_add_u64 v[142:143], s[4:5], 0, v[142:143]
	v_cvt_pk_bf16_f32 v144, v144, s0
	global_store_short v[142:143], v144, off
	v_mul_f32_e32 v144, v148, v145
	v_cvt_pk_bf16_f32 v144, v144, s0
	v_add_co_u32_e64 v146, s[0:1], s36, v160
	v_or_b32_e32 v140, v140, v193
	s_nop 0
	v_addc_co_u32_e64 v147, s[0:1], 0, v161, s[0:1]
	global_store_short v[146:147], v144, off offset:256
	v_mul_f32_e32 v144, v150, v145
	v_cvt_pk_bf16_f32 v146, v144, s0
	v_add_co_u32_e64 v144, s[0:1], s36, v142
	s_nop 1
	v_addc_co_u32_e64 v145, s[0:1], 0, v143, s[0:1]
	global_store_short v[144:145], v146, off offset:256
	v_mul_f32_e32 v144, v148, v152
	v_cvt_pk_bf16_f32 v146, v144, s0
	v_add_co_u32_e64 v144, s[0:1], s21, v160
	s_nop 1
	v_addc_co_u32_e64 v145, s[0:1], 0, v161, s[0:1]
	global_store_short v[144:145], v146, off offset:512
	v_mul_f32_e32 v144, v150, v152
	v_cvt_pk_bf16_f32 v146, v144, s0
	v_add_co_u32_e64 v144, s[0:1], s21, v142
	s_nop 1
	v_addc_co_u32_e64 v145, s[0:1], 0, v143, s[0:1]
	global_store_short v[144:145], v146, off offset:512
	v_mul_f32_e32 v144, v148, v155
	v_cvt_pk_bf16_f32 v146, v144, s0
	v_add_co_u32_e64 v144, s[0:1], s37, v160
	s_nop 1
	v_addc_co_u32_e64 v145, s[0:1], 0, v161, s[0:1]
	global_store_short v[144:145], v146, off offset:768
	v_mul_f32_e32 v144, v150, v155
	v_cvt_pk_bf16_f32 v144, v144, s0
	v_add_co_u32_e64 v142, s[0:1], s37, v142
	s_nop 1
	v_addc_co_u32_e64 v143, s[0:1], 0, v143, s[0:1]
	global_store_short v[142:143], v144, off offset:768
	v_mad_u64_u32 v[142:143], s[0:1], v140, s43, v[2:3]
	v_mad_i32_i24 v143, v141, s43, v143
	v_lshlrev_b64 v[140:141], 1, v[142:143]
	v_mul_f32_e32 v2, v148, v158
	v_lshl_add_u64 v[142:143], s[16:17], 0, v[140:141]
	v_cvt_pk_bf16_f32 v2, v2, s0
	global_store_short v[142:143], v2, off
	v_mul_f32_e32 v2, v150, v158
	v_lshl_add_u64 v[140:141], s[4:5], 0, v[140:141]
	v_cvt_pk_bf16_f32 v2, v2, s0
	global_store_short v[140:141], v2, off
	v_mul_f32_e32 v2, v148, v149
	v_cvt_pk_bf16_f32 v2, v2, s0
	v_add_co_u32_e64 v144, s[0:1], s36, v142
	s_nop 1
	v_addc_co_u32_e64 v145, s[0:1], 0, v143, s[0:1]
	global_store_short v[144:145], v2, off offset:256
	v_mul_f32_e32 v2, v150, v149
	v_cvt_pk_bf16_f32 v2, v2, s0
	v_add_co_u32_e64 v144, s[0:1], s36, v140
	s_nop 1
	v_addc_co_u32_e64 v145, s[0:1], 0, v141, s[0:1]
	global_store_short v[144:145], v2, off offset:256
	v_mul_f32_e32 v2, v148, v156
	v_cvt_pk_bf16_f32 v2, v2, s0
	v_add_co_u32_e64 v144, s[0:1], s21, v142
	s_nop 1
	v_addc_co_u32_e64 v145, s[0:1], 0, v143, s[0:1]
	global_store_short v[144:145], v2, off offset:512
	v_mul_f32_e32 v2, v150, v156
	v_cvt_pk_bf16_f32 v2, v2, s0
	v_add_co_u32_e64 v144, s[0:1], s21, v140
	s_nop 1
	v_addc_co_u32_e64 v145, s[0:1], 0, v141, s[0:1]
	global_store_short v[144:145], v2, off offset:512
	v_mul_f32_e32 v2, v148, v151
	v_cvt_pk_bf16_f32 v2, v2, s0
	v_add_co_u32_e64 v142, s[0:1], s37, v142
	s_nop 1
	v_addc_co_u32_e64 v143, s[0:1], 0, v143, s[0:1]
	global_store_short v[142:143], v2, off offset:768
	v_mul_f32_e32 v2, v150, v151
	v_cvt_pk_bf16_f32 v2, v2, s0
	v_add_co_u32_e64 v140, s[0:1], s37, v140
	v_pk_mul_f32 v[142:143], v[72:73], v[192:193] op_sel_hi:[1,0]
	s_nop 0
	v_addc_co_u32_e64 v141, s[0:1], 0, v141, s[0:1]
	global_store_short v[140:141], v2, off offset:768
	v_pk_mul_f32 v[140:141], v[74:75], v[192:193] op_sel_hi:[1,0]
	v_pk_mul_f32 v[144:145], v[136:137], v[142:143] op_sel:[1,1] op_sel_hi:[1,0]
	v_mov_b32_e32 v2, v139
	v_pk_fma_f32 v[146:147], v[136:137], v[142:143], v[144:145] op_sel_hi:[0,1,1] neg_lo:[0,0,1] neg_hi:[0,0,1]
	v_pk_fma_f32 v[136:137], v[136:137], v[142:143], v[144:145] op_sel_hi:[0,1,1]
	v_pk_mul_f32 v[142:143], v[2:3], v[140:141] op_sel:[0,1] op_sel_hi:[0,0]
	v_pk_fma_f32 v[144:145], v[138:139], v[140:141], v[142:143] op_sel_hi:[0,1,1] neg_lo:[0,0,1] neg_hi:[0,0,1]
	v_pk_fma_f32 v[138:139], v[138:139], v[140:141], v[142:143] op_sel_hi:[0,1,1]
	v_pk_mul_f32 v[142:143], v[68:69], v[192:193] op_sel_hi:[1,0]
	v_pk_mul_f32 v[140:141], v[70:71], v[192:193] op_sel_hi:[1,0]
	v_pk_mul_f32 v[148:149], v[132:133], v[142:143] op_sel:[1,1] op_sel_hi:[1,0]
	v_mov_b32_e32 v2, v135
	v_pk_fma_f32 v[150:151], v[132:133], v[142:143], v[148:149] op_sel_hi:[0,1,1] neg_lo:[0,0,1] neg_hi:[0,0,1]
	v_pk_fma_f32 v[142:143], v[132:133], v[142:143], v[148:149] op_sel_hi:[0,1,1]
	v_pk_mul_f32 v[132:133], v[2:3], v[140:141] op_sel:[0,1] op_sel_hi:[0,0]
	v_pk_fma_f32 v[148:149], v[134:135], v[140:141], v[132:133] op_sel_hi:[0,1,1] neg_lo:[0,0,1] neg_hi:[0,0,1]
	v_pk_fma_f32 v[140:141], v[134:135], v[140:141], v[132:133] op_sel_hi:[0,1,1]
	v_lshlrev_b64 v[132:133], 10, v[190:191]
	v_lshl_add_u64 v[132:133], s[94:95], 0, v[132:133]
	v_lshl_add_u64 v[152:153], v[132:133], 0, v[188:189]
	v_add_co_u32_e64 v152, s[0:1], s47, v152
	v_add_u32_e32 v2, 0x80, v197
	v_cvt_pk_bf16_f32 v132, v146, v137
	v_cvt_pk_bf16_f32 v133, v144, v139
	v_cvt_pk_bf16_f32 v134, v150, v143
	v_cvt_pk_bf16_f32 v135, v148, v141
	v_addc_co_u32_e64 v153, s[0:1], 0, v153, s[0:1]
	v_cndmask_b32_e32 v2, v244, v2, vcc
	global_store_dwordx4 v[152:153], v[132:135], off offset:3072
	s_lshr_b32 s0, s3, 4
	s_nop 0
	v_and_b32_e32 v133, 0x7f, v2
	v_mov_b32_e32 v132, s0
	v_bitop3_b32 v134, v2, s42, v2 bitop3:0xc
	v_cvt_f32_ubyte0_e32 v133, v133
	v_cndmask_b32_e32 v132, v132, v199, vcc
	v_cvt_f32_ubyte0_e32 v134, v134
	v_mul_f32_e64 v133, v133, -v214
	v_mul_f32_e64 v134, v134, -v212
	v_mul_f32_e32 v133, 0x3fb8aa3b, v133
	v_lshl_or_b32 v132, v132, 3, s2
	v_mul_f32_e32 v134, 0x3fb8aa3b, v134
	v_exp_f32_e32 v140, v133
	v_ashrrev_i32_e32 v133, 31, v132
	v_exp_f32_e32 v138, v134
	v_lshlrev_b64 v[132:133], 6, v[132:133]
	v_or_b32_e32 v134, v132, v216
	v_mad_u64_u32 v[134:135], s[0:1], v134, s43, v[2:3]
	v_mad_i32_i24 v135, v133, s43, v135
	v_lshlrev_b64 v[134:135], 1, v[134:135]
	v_mul_f32_e32 v136, v138, v146
	v_lshl_add_u64 v[152:153], s[16:17], 0, v[134:135]
	v_cvt_pk_bf16_f32 v136, v136, s0
	global_store_short v[152:153], v136, off
	v_mul_f32_e32 v136, v140, v146
	v_lshl_add_u64 v[134:135], s[4:5], 0, v[134:135]
	v_cvt_pk_bf16_f32 v136, v136, s0
	global_store_short v[134:135], v136, off
	v_mul_f32_e32 v136, v138, v137
	v_add_co_u32_e32 v146, vcc, s36, v152
	v_cvt_pk_bf16_f32 v136, v136, s0
	s_nop 0
	v_addc_co_u32_e32 v147, vcc, 0, v153, vcc
	global_store_short v[146:147], v136, off offset:256
	v_mul_f32_e32 v136, v140, v137
	v_cvt_pk_bf16_f32 v142, v136, s0
	v_add_co_u32_e32 v136, vcc, s36, v134
	v_or_b32_e32 v132, v132, v193
	s_nop 0
	v_addc_co_u32_e32 v137, vcc, 0, v135, vcc
	global_store_short v[136:137], v142, off offset:256
	v_mul_f32_e32 v136, v138, v144
	v_cvt_pk_bf16_f32 v142, v136, s0
	v_add_co_u32_e32 v136, vcc, s21, v152
	s_nop 1
	v_addc_co_u32_e32 v137, vcc, 0, v153, vcc
	global_store_short v[136:137], v142, off offset:512
	v_mul_f32_e32 v136, v140, v144
	v_cvt_pk_bf16_f32 v142, v136, s0
	v_add_co_u32_e32 v136, vcc, s21, v134
	s_nop 1
	v_addc_co_u32_e32 v137, vcc, 0, v135, vcc
	global_store_short v[136:137], v142, off offset:512
	v_mul_f32_e32 v136, v138, v139
	v_cvt_pk_bf16_f32 v142, v136, s0
	v_add_co_u32_e32 v136, vcc, s37, v152
	s_nop 1
	v_addc_co_u32_e32 v137, vcc, 0, v153, vcc
	global_store_short v[136:137], v142, off offset:768
	v_mul_f32_e32 v136, v140, v139
	v_add_co_u32_e32 v134, vcc, s37, v134
	v_cvt_pk_bf16_f32 v136, v136, s0
	s_nop 0
	v_addc_co_u32_e32 v135, vcc, 0, v135, vcc
	global_store_short v[134:135], v136, off offset:768
	v_mad_u64_u32 v[134:135], s[0:1], v132, s43, v[2:3]
	v_mad_i32_i24 v135, v133, s43, v135
	v_lshlrev_b64 v[132:133], 1, v[134:135]
	v_mul_f32_e32 v2, v138, v150
	v_lshl_add_u64 v[134:135], s[16:17], 0, v[132:133]
	v_cvt_pk_bf16_f32 v2, v2, s0
	global_store_short v[134:135], v2, off
	v_mul_f32_e32 v2, v140, v150
	v_lshl_add_u64 v[132:133], s[4:5], 0, v[132:133]
	v_cvt_pk_bf16_f32 v2, v2, s0
	global_store_short v[132:133], v2, off
	v_mul_f32_e32 v2, v138, v143
	v_add_co_u32_e32 v136, vcc, s36, v134
	v_cvt_pk_bf16_f32 v2, v2, s0
	s_nop 0
	v_addc_co_u32_e32 v137, vcc, 0, v135, vcc
	global_store_short v[136:137], v2, off offset:256
	v_mul_f32_e32 v2, v140, v143
	v_add_co_u32_e32 v136, vcc, s36, v132
	v_cvt_pk_bf16_f32 v2, v2, s0
	s_nop 0
	v_addc_co_u32_e32 v137, vcc, 0, v133, vcc
	global_store_short v[136:137], v2, off offset:256
	v_mul_f32_e32 v2, v138, v148
	v_add_co_u32_e32 v136, vcc, s21, v134
	v_cvt_pk_bf16_f32 v2, v2, s0
	s_nop 0
	v_addc_co_u32_e32 v137, vcc, 0, v135, vcc
	global_store_short v[136:137], v2, off offset:512
	v_mul_f32_e32 v2, v140, v148
	v_add_co_u32_e32 v136, vcc, s21, v132
	v_cvt_pk_bf16_f32 v2, v2, s0
	s_nop 0
	v_addc_co_u32_e32 v137, vcc, 0, v133, vcc
	global_store_short v[136:137], v2, off offset:512
	v_mul_f32_e32 v2, v138, v141
	v_add_co_u32_e32 v134, vcc, 0x3000, v134
	v_cvt_pk_bf16_f32 v2, v2, s0
	s_nop 0
	v_addc_co_u32_e32 v135, vcc, 0, v135, vcc
	global_store_short v[134:135], v2, off offset:768
	v_mul_f32_e32 v2, v140, v141
	v_add_co_u32_e32 v132, vcc, 0x3000, v132
	v_cvt_pk_bf16_f32 v2, v2, s0
	s_nop 0
	v_addc_co_u32_e32 v133, vcc, 0, v133, vcc
	global_store_short v[132:133], v2, off offset:768

.LBB0_166:
	s_bitcmp1_b32 s74, 7
	s_cbranch_scc1 .LBB0_45
	s_nop 1
	v_mov_b32_e32 v68, v4
	v_mov_b32_e32 v69, v5
	v_mov_b32_e32 v70, v6
	v_mov_b32_e32 v71, v7
	v_mov_b32_e32 v72, v8
	v_mov_b32_e32 v73, v9
	v_mov_b32_e32 v74, v10
	v_mov_b32_e32 v75, v11
	v_mov_b32_e32 v76, v12
	v_mov_b32_e32 v77, v13
	v_mov_b32_e32 v78, v14
	v_mov_b32_e32 v79, v15
	v_mov_b32_e32 v80, v16
	v_mov_b32_e32 v81, v17
	v_mov_b32_e32 v82, v18
	v_mov_b32_e32 v83, v19
	v_mov_b32_e32 v84, v20
	v_mov_b32_e32 v85, v21
	v_mov_b32_e32 v86, v22
	v_mov_b32_e32 v87, v23
	v_mov_b32_e32 v88, v24
	v_mov_b32_e32 v89, v25
	v_mov_b32_e32 v90, v26
	v_mov_b32_e32 v91, v27
	v_mov_b32_e32 v92, v28
	v_mov_b32_e32 v93, v29
	v_mov_b32_e32 v94, v30
	v_mov_b32_e32 v95, v31
	v_mov_b32_e32 v96, v32
	v_mov_b32_e32 v97, v33
	v_mov_b32_e32 v98, v34
	v_mov_b32_e32 v99, v35
	v_mov_b32_e32 v100, v36
	v_mov_b32_e32 v101, v37
	v_mov_b32_e32 v102, v38
	v_mov_b32_e32 v103, v39
	v_mov_b32_e32 v104, v40
	v_mov_b32_e32 v105, v41
	v_mov_b32_e32 v106, v42
	v_mov_b32_e32 v107, v43
	v_mov_b32_e32 v108, v44
	v_mov_b32_e32 v109, v45
	v_mov_b32_e32 v110, v46
	v_mov_b32_e32 v111, v47
	v_mov_b32_e32 v112, v48
	v_mov_b32_e32 v113, v49
	v_mov_b32_e32 v114, v50
	v_mov_b32_e32 v115, v51
	v_mov_b32_e32 v116, v52
	v_mov_b32_e32 v117, v53
	v_mov_b32_e32 v118, v54
	v_mov_b32_e32 v119, v55
	v_mov_b32_e32 v120, v56
	v_mov_b32_e32 v121, v57
	v_mov_b32_e32 v122, v58
	v_mov_b32_e32 v123, v59
	v_mov_b32_e32 v124, v60
	v_mov_b32_e32 v125, v61
	v_mov_b32_e32 v126, v62
	v_mov_b32_e32 v127, v63
	v_mov_b32_e32 v128, v64
	v_mov_b32_e32 v129, v65
	v_mov_b32_e32 v130, v66
	v_mov_b32_e32 v131, v67
	s_or_b32 s74, s74, 0x80
	s_cmpk_lt_u32 s74, 0x200
	s_mov_b32 s2, 0
	s_cbranch_scc1 .LBB0_60
	s_branch .Lsec_chain
